# hidden weight-transpose slots in the in-proj GEMM loop: barrier no longer waits for the transposed-weight stores to drain (vmcnt(0) -> lgkmcnt(0))
# baseline (speedup 1.0000x reference)
; __device__ __forceinline__ unsigned cvt_pk_bf16(float lo, float hi) { unsigned r; asm volatile("v_cvt_pk_bf16_f32 %0, %1, %2" : "=v"(r) : "v"(lo), "v"(hi)); return r; }
; template <int PERMT>
; __device__ __forceinline__ void transpose_job(const float* __restrict__ src, bf16_t* __restrict__ dst, int K, int N, int Npad, const float* __restrict__ kscale, unsigned char* lds_g, int first, int stride) {
;     ...
;         { const int n = tid >> 1, ks = tid & 1;
;           if (n0 + n < N) { bf16_t* dp = dst + (size_t)dst_row<PERMT>(n0 + n) * K + k0 + 32 * ks;
; #pragma unroll
;             for (int eb = 0; eb < 4; ++eb) { float v[8];
; #pragma unroll
;               for (int e = 0; e < 8; ++e) v[e] = T[(32 * ks + 8 * eb + e) * 257 + n];
;               u32x4 w; w.x = cvt_pk_bf16(v[0], v[1]); w.y = cvt_pk_bf16(v[2], v[3]); w.z = cvt_pk_bf16(v[4], v[5]); w.w = cvt_pk_bf16(v[6], v[7]);
;               *(u32x4*)(dp + 8 * eb) = w; } } }
;         __syncthreads();
.LBB0_668:
	v_cvt_pk_bf16_f32 v6, v6, v7
	v_cvt_pk_bf16_f32 v7, v8, v9
	v_cvt_pk_bf16_f32 v8, v2, v3
	v_cvt_pk_bf16_f32 v9, v4, v5
	flat_store_dwordx4 v[12:13], v[6:9] offset:256
	s_waitcnt lgkmcnt(0)
	s_barrier

; __device__ __forceinline__ u32x4 pack8(const f32x4 v0, const f32x4 v1) { u32x4 w; w.x = cvt_pk_bf16(v0[0], v0[1]); w.y = cvt_pk_bf16(v0[2], v0[3]); w.z = cvt_pk_bf16(v1[0], v1[1]); w.w = cvt_pk_bf16(v1[2], v1[3]); return w; }
;     __device__ __forceinline__ void operator()(const f32x4 (&acc)[2][2][4][2], const Unit& u, int wr, int wc, int fr, int fq) const {
;         const int row0 = u.pm * BM + wr * 64 + fr, cin = wc * 32 + 8 * fq;
;         f32x4 q2[2][4];
; #pragma unroll
;         for (int ai = 0; ai < 2; ++ai)
; #pragma unroll
;             for (int m = 0; m < 4; ++m) q2[ai][m] = *(const f32x4*)(ssq + (size_t)(row0 + ai * HALF + m * 16) * 12 + 8);
; #pragma unroll
;         for (int ai = 0; ai < 2; ++ai)
; #pragma unroll
;             for (int m = 0; m < 4; ++m) { const int row = row0 + ai * HALF + m * 16; const f32x4 a = q2[ai][m];
;                 const float s = 1.0f / sqrtf(((a[0] + a[1]) + (a[2] + a[3])) * (1.0f / 256.0f) + 1e-6f);
;                 *(u32x4*)(Kb + (size_t)row * ldk + 192 * u.pn + cin) = pack8(acc[ai][0][m][0] * s, acc[ai][0][m][1] * s);
;                 *(u32x4*)(Vb + (size_t)row * ldv + 128 * u.pn + cin) = pack8(acc[ai][1][m][0] * s, acc[ai][1][m][1] * s); }
.LBB0_680:
	v_lshl_add_u32 v194, s28, 8, v170
	v_mad_i64_i32 v[114:115], s[0:1], v194, 48, s[16:17]
	flat_load_dwordx4 v[180:183], v[114:115] offset:32
	v_or_b32_e32 v179, 16, v194
	v_mad_i64_i32 v[114:115], s[0:1], v179, 48, s[16:17]
	flat_load_dwordx4 v[154:157], v[114:115] offset:32
	v_or_b32_e32 v178, 32, v194
	v_mad_i64_i32 v[114:115], s[0:1], v178, 48, s[16:17]
	flat_load_dwordx4 v[150:153], v[114:115] offset:32
	v_or_b32_e32 v177, 48, v194
	v_mad_i64_i32 v[114:115], s[0:1], v177, 48, s[16:17]
	v_add_u32_e32 v176, 0x80, v194
	flat_load_dwordx4 v[146:149], v[114:115] offset:32
	v_mad_i64_i32 v[114:115], s[0:1], v176, 48, s[16:17]
	v_add_u32_e32 v175, 0x90, v194
	flat_load_dwordx4 v[142:145], v[114:115] offset:32
	v_mad_i64_i32 v[114:115], s[0:1], v175, 48, s[16:17]
	v_add_u32_e32 v174, 0xa0, v194
	flat_load_dwordx4 v[130:133], v[114:115] offset:32
	v_mad_i64_i32 v[114:115], s[0:1], v174, 48, s[16:17]
	v_add_u32_e32 v173, 0xb0, v194
	flat_load_dwordx4 v[118:121], v[114:115] offset:32
	v_mad_i64_i32 v[114:115], s[0:1], v173, 48, s[16:17]
	flat_load_dwordx4 v[114:117], v[114:115] offset:32
	s_mul_i32 s90, s48, 0xc0
	s_lshl_b64 s[28:29], s[90:91], 1
	s_lshl_b32 s90, s48, 8
	s_waitcnt vmcnt(0) lgkmcnt(0)
	v_mov_b32_e32 v184, v181
	v_mov_b32_e32 v185, v182
	v_mov_b32_e32 v181, v183
	v_pk_add_f32 v[180:181], v[184:185], v[180:181]
	s_nop 0
	v_add_f32_e32 v180, v180, v181
	v_fmamk_f32 v180, v180, 0x3b800000, v218
	v_cmp_gt_f32_e32 vcc, s77, v180
	v_mul_f32_e32 v181, 0x4f800000, v180
	s_nop 0
	v_cndmask_b32_e32 v180, v180, v181, vcc
	v_sqrt_f32_e32 v181, v180
	s_nop 0
	v_add_u32_e32 v182, -1, v181
	v_fma_f32 v183, -v182, v181, v180
	v_cmp_ge_f32_e64 s[0:1], 0, v183
	v_add_u32_e32 v183, 1, v181
	s_nop 0
	v_cndmask_b32_e64 v182, v181, v182, s[0:1]
	v_fma_f32 v181, -v183, v181, v180
	v_cmp_lt_f32_e64 s[0:1], 0, v181
	s_nop 1
	v_cndmask_b32_e64 v181, v182, v183, s[0:1]
	v_mul_f32_e32 v182, 0x37800000, v181
	v_cndmask_b32_e32 v181, v181, v182, vcc
	v_cmp_class_f32_e32 vcc, v180, v219
	s_nop 1
	v_cndmask_b32_e32 v180, v181, v180, vcc
	v_div_scale_f32 v181, s[0:1], v180, v180, 1.0
	v_rcp_f32_e32 v182, v181
	s_nop 0
	v_fma_f32 v183, -v181, v182, 1.0
	v_fmac_f32_e32 v182, v183, v182
	v_div_scale_f32 v183, vcc, 1.0, v180, 1.0
	v_mul_f32_e32 v184, v183, v182
	v_fma_f32 v185, -v181, v184, v183
	v_fmac_f32_e32 v184, v185, v182
	v_fma_f32 v181, -v181, v184, v183
	v_div_fmas_f32 v181, v181, v182, v184
	v_div_fixup_f32 v180, v181, v180, 1.0
	v_pk_mul_f32 v[134:135], v[134:135], v[180:181] op_sel_hi:[1,0]
	v_pk_mul_f32 v[182:183], v[136:137], v[180:181] op_sel_hi:[1,0]
	v_pk_mul_f32 v[140:141], v[140:141], v[180:181] op_sel_hi:[1,0]
	v_pk_mul_f32 v[138:139], v[138:139], v[180:181] op_sel_hi:[1,0]
	v_cvt_pk_bf16_f32 v136, v134, v135
	v_mov_b64_e32 v[134:135], s[12:13]
	v_cvt_pk_bf16_f32 v137, v182, v183
	v_cvt_pk_bf16_f32 v138, v138, v139
	v_cvt_pk_bf16_f32 v139, v140, v141
	v_mad_i64_i32 v[140:141], s[0:1], v194, s87, v[134:135]
	v_lshl_add_u64 v[140:141], v[140:141], 0, s[28:29]
	v_lshl_add_u64 v[140:141], v[140:141], 0, v[0:1]
	v_pk_mul_f32 v[126:127], v[126:127], v[180:181] op_sel_hi:[1,0]
	v_pk_mul_f32 v[122:123], v[122:123], v[180:181] op_sel_hi:[1,0]
	flat_store_dwordx4 v[140:141], v[136:139]
	v_pk_mul_f32 v[128:129], v[128:129], v[180:181] op_sel_hi:[1,0]
	s_nop 0
	v_pk_mul_f32 v[136:137], v[124:125], v[180:181] op_sel_hi:[1,0]
	v_cvt_pk_bf16_f32 v124, v126, v127
	v_cvt_pk_bf16_f32 v125, v128, v129
	v_cvt_pk_bf16_f32 v126, v122, v123
	v_mov_b64_e32 v[122:123], s[14:15]
	v_mad_i64_i32 v[128:129], s[0:1], v194, s33, v[122:123]
	v_lshl_add_u64 v[128:129], v[128:129], 0, s[90:91]
	v_lshl_add_u64 v[128:129], v[128:129], 0, v[0:1]
	v_cvt_pk_bf16_f32 v127, v136, v137
	flat_store_dwordx4 v[128:129], v[124:127]
	s_nop 1
	v_mov_b32_e32 v124, v155
	v_mov_b32_e32 v125, v156
	v_mov_b32_e32 v155, v157
	v_pk_add_f32 v[124:125], v[124:125], v[154:155]
	s_nop 0
	v_add_f32_e32 v124, v124, v125
	v_fmamk_f32 v124, v124, 0x3b800000, v218
	v_cmp_gt_f32_e32 vcc, s77, v124
	v_mul_f32_e32 v125, 0x4f800000, v124
	s_nop 0
	v_cndmask_b32_e32 v124, v124, v125, vcc
	v_sqrt_f32_e32 v125, v124
	s_nop 0
	v_add_u32_e32 v126, -1, v125
	v_fma_f32 v127, -v126, v125, v124
	v_cmp_ge_f32_e64 s[0:1], 0, v127
	v_add_u32_e32 v127, 1, v125
	s_nop 0
	v_cndmask_b32_e64 v126, v125, v126, s[0:1]
	v_fma_f32 v125, -v127, v125, v124
	v_cmp_lt_f32_e64 s[0:1], 0, v125
	s_nop 1
	v_cndmask_b32_e64 v125, v126, v127, s[0:1]
	v_mul_f32_e32 v126, 0x37800000, v125
	v_cndmask_b32_e32 v125, v125, v126, vcc
	v_cmp_class_f32_e32 vcc, v124, v219
	s_nop 1
	v_cndmask_b32_e32 v124, v125, v124, vcc
	v_div_scale_f32 v125, s[0:1], v124, v124, 1.0
	v_rcp_f32_e32 v126, v125
	s_nop 0
	v_fma_f32 v127, -v125, v126, 1.0
	v_fmac_f32_e32 v126, v127, v126
	v_div_scale_f32 v127, vcc, 1.0, v124, 1.0
	v_mul_f32_e32 v128, v127, v126
	v_fma_f32 v129, -v125, v128, v127
	v_fmac_f32_e32 v128, v129, v126
	v_fma_f32 v125, -v125, v128, v127
	v_div_fmas_f32 v125, v125, v126, v128
	v_div_fixup_f32 v124, v125, v124, 1.0
	v_pk_mul_f32 v[110:111], v[110:111], v[124:125] op_sel_hi:[1,0]
	v_pk_mul_f32 v[126:127], v[108:109], v[124:125] op_sel_hi:[1,0]
	v_pk_mul_f32 v[108:109], v[106:107], v[124:125] op_sel_hi:[1,0]
	v_cvt_pk_bf16_f32 v106, v110, v111
	v_mad_i64_i32 v[110:111], s[0:1], v179, s87, v[134:135]
	v_lshl_add_u64 v[110:111], v[110:111], 0, s[28:29]
	v_pk_mul_f32 v[112:113], v[112:113], v[124:125] op_sel_hi:[1,0]
	v_lshl_add_u64 v[110:111], v[110:111], 0, v[0:1]
	v_cvt_pk_bf16_f32 v107, v112, v113
	v_pk_mul_f32 v[102:103], v[102:103], v[124:125] op_sel_hi:[1,0]
	v_cvt_pk_bf16_f32 v108, v108, v109
	v_cvt_pk_bf16_f32 v109, v126, v127
; __device__ __forceinline__ u32x4 pack8(const f32x4 v0, const f32x4 v1) { u32x4 w; w.x = cvt_pk_bf16(v0[0], v0[1]); w.y = cvt_pk_bf16(v0[2], v0[3]); w.z = cvt_pk_bf16(v1[0], v1[1]); w.w = cvt_pk_bf16(v1[2], v1[3]); return w; }
;     __device__ __forceinline__ void operator()(const f32x4 (&acc)[2][2][4][2], const Unit& u, int wr, int wc, int fr, int fq) const {
;     ...
;         for (int ai = 0; ai < 2; ++ai)
; #pragma unroll
;             for (int m = 0; m < 4; ++m) { const int row = row0 + ai * HALF + m * 16; const f32x4 a = q2[ai][m];
;                 const float s = 1.0f / sqrtf(((a[0] + a[1]) + (a[2] + a[3])) * (1.0f / 256.0f) + 1e-6f);
;                 *(u32x4*)(Kb + (size_t)row * ldk + 192 * u.pn + cin) = pack8(acc[ai][0][m][0] * s, acc[ai][0][m][1] * s);
;                 *(u32x4*)(Vb + (size_t)row * ldv + 128 * u.pn + cin) = pack8(acc[ai][1][m][0] * s, acc[ai][1][m][1] * s); }
	flat_store_dwordx4 v[110:111], v[106:109]
	v_pk_mul_f32 v[104:105], v[104:105], v[124:125] op_sel_hi:[1,0]
	s_nop 0
	v_pk_mul_f32 v[106:107], v[100:101], v[124:125] op_sel_hi:[1,0]
	v_pk_mul_f32 v[100:101], v[98:99], v[124:125] op_sel_hi:[1,0]
	v_cvt_pk_bf16_f32 v98, v102, v103
	v_mad_i64_i32 v[102:103], s[0:1], v179, s33, v[122:123]
	v_lshl_add_u64 v[102:103], v[102:103], 0, s[90:91]
	v_cvt_pk_bf16_f32 v99, v104, v105
	v_lshl_add_u64 v[102:103], v[102:103], 0, v[0:1]
	v_cvt_pk_bf16_f32 v100, v100, v101
	v_cvt_pk_bf16_f32 v101, v106, v107
	flat_store_dwordx4 v[102:103], v[98:101]
	s_nop 1
	v_mov_b32_e32 v98, v151
	v_mov_b32_e32 v99, v152
	v_mov_b32_e32 v151, v153
	v_pk_add_f32 v[98:99], v[98:99], v[150:151]
	s_nop 0
	v_add_f32_e32 v98, v98, v99
	v_fmamk_f32 v98, v98, 0x3b800000, v218
	v_cmp_gt_f32_e32 vcc, s77, v98
	v_mul_f32_e32 v99, 0x4f800000, v98
	s_nop 0
	v_cndmask_b32_e32 v98, v98, v99, vcc
	v_sqrt_f32_e32 v99, v98
	s_nop 0
	v_add_u32_e32 v100, -1, v99
	v_fma_f32 v101, -v100, v99, v98
	v_cmp_ge_f32_e64 s[0:1], 0, v101
	v_add_u32_e32 v101, 1, v99
	s_nop 0
	v_cndmask_b32_e64 v100, v99, v100, s[0:1]
	v_fma_f32 v99, -v101, v99, v98
	v_cmp_lt_f32_e64 s[0:1], 0, v99
	s_nop 1
	v_cndmask_b32_e64 v99, v100, v101, s[0:1]
	v_mul_f32_e32 v100, 0x37800000, v99
	v_cndmask_b32_e32 v99, v99, v100, vcc
	v_cmp_class_f32_e32 vcc, v98, v219
	s_nop 1
	v_cndmask_b32_e32 v98, v99, v98, vcc
	v_div_scale_f32 v99, s[0:1], v98, v98, 1.0
	v_rcp_f32_e32 v100, v99
	s_nop 0
	v_fma_f32 v101, -v99, v100, 1.0
	v_fmac_f32_e32 v100, v101, v100
	v_div_scale_f32 v101, vcc, 1.0, v98, 1.0
	v_mul_f32_e32 v102, v101, v100
	v_fma_f32 v103, -v99, v102, v101
	v_fmac_f32_e32 v102, v103, v100
	v_fma_f32 v99, -v99, v102, v101
	v_div_fmas_f32 v99, v99, v100, v102
	v_div_fixup_f32 v98, v99, v98, 1.0
	v_pk_mul_f32 v[94:95], v[94:95], v[98:99] op_sel_hi:[1,0]
	v_pk_mul_f32 v[100:101], v[92:93], v[98:99] op_sel_hi:[1,0]
	v_pk_mul_f32 v[92:93], v[90:91], v[98:99] op_sel_hi:[1,0]
	v_cvt_pk_bf16_f32 v90, v94, v95
	v_mad_i64_i32 v[94:95], s[0:1], v178, s87, v[134:135]
	v_lshl_add_u64 v[94:95], v[94:95], 0, s[28:29]
	v_pk_mul_f32 v[96:97], v[96:97], v[98:99] op_sel_hi:[1,0]
	v_lshl_add_u64 v[94:95], v[94:95], 0, v[0:1]
	v_cvt_pk_bf16_f32 v91, v96, v97
	v_pk_mul_f32 v[86:87], v[86:87], v[98:99] op_sel_hi:[1,0]
	v_cvt_pk_bf16_f32 v92, v92, v93
	v_cvt_pk_bf16_f32 v93, v100, v101
	flat_store_dwordx4 v[94:95], v[90:93]
	v_pk_mul_f32 v[88:89], v[88:89], v[98:99] op_sel_hi:[1,0]
	s_nop 0
	v_pk_mul_f32 v[90:91], v[84:85], v[98:99] op_sel_hi:[1,0]
	v_pk_mul_f32 v[84:85], v[82:83], v[98:99] op_sel_hi:[1,0]
	v_cvt_pk_bf16_f32 v82, v86, v87
	v_mad_i64_i32 v[86:87], s[0:1], v178, s33, v[122:123]
	v_lshl_add_u64 v[86:87], v[86:87], 0, s[90:91]
	v_cvt_pk_bf16_f32 v83, v88, v89
	v_lshl_add_u64 v[86:87], v[86:87], 0, v[0:1]
	v_cvt_pk_bf16_f32 v84, v84, v85
	v_cvt_pk_bf16_f32 v85, v90, v91
	flat_store_dwordx4 v[86:87], v[82:85]
	s_nop 1
	v_mov_b32_e32 v82, v147
	v_mov_b32_e32 v83, v148
	v_mov_b32_e32 v147, v149
	v_pk_add_f32 v[82:83], v[82:83], v[146:147]
	s_nop 0
	v_add_f32_e32 v82, v82, v83
	v_fmamk_f32 v82, v82, 0x3b800000, v218
	v_cmp_gt_f32_e32 vcc, s77, v82
	v_mul_f32_e32 v83, 0x4f800000, v82
	s_nop 0
	v_cndmask_b32_e32 v82, v82, v83, vcc
	v_sqrt_f32_e32 v83, v82
	s_nop 0
	v_add_u32_e32 v84, -1, v83
	v_fma_f32 v85, -v84, v83, v82
	v_cmp_ge_f32_e64 s[0:1], 0, v85
	v_add_u32_e32 v85, 1, v83
	s_nop 0
	v_cndmask_b32_e64 v84, v83, v84, s[0:1]
	v_fma_f32 v83, -v85, v83, v82
	v_cmp_lt_f32_e64 s[0:1], 0, v83
	s_nop 1
	v_cndmask_b32_e64 v83, v84, v85, s[0:1]
	v_mul_f32_e32 v84, 0x37800000, v83
	v_cndmask_b32_e32 v83, v83, v84, vcc
	v_cmp_class_f32_e32 vcc, v82, v219
	s_nop 1
	v_cndmask_b32_e32 v82, v83, v82, vcc
	v_div_scale_f32 v83, s[0:1], v82, v82, 1.0
	v_rcp_f32_e32 v84, v83
	s_nop 0
	v_fma_f32 v85, -v83, v84, 1.0
	v_fmac_f32_e32 v84, v85, v84
	v_div_scale_f32 v85, vcc, 1.0, v82, 1.0
	v_mul_f32_e32 v86, v85, v84
	v_fma_f32 v87, -v83, v86, v85
	v_fmac_f32_e32 v86, v87, v84
	v_fma_f32 v83, -v83, v86, v85
	v_div_fmas_f32 v83, v83, v84, v86
	v_div_fixup_f32 v82, v83, v82, 1.0
	v_pk_mul_f32 v[78:79], v[78:79], v[82:83] op_sel_hi:[1,0]
	v_pk_mul_f32 v[84:85], v[76:77], v[82:83] op_sel_hi:[1,0]
	v_pk_mul_f32 v[76:77], v[74:75], v[82:83] op_sel_hi:[1,0]
	v_cvt_pk_bf16_f32 v74, v78, v79
	v_mad_i64_i32 v[78:79], s[0:1], v177, s87, v[134:135]
	v_lshl_add_u64 v[78:79], v[78:79], 0, s[28:29]
	v_pk_mul_f32 v[80:81], v[80:81], v[82:83] op_sel_hi:[1,0]
	v_lshl_add_u64 v[78:79], v[78:79], 0, v[0:1]
	v_cvt_pk_bf16_f32 v75, v80, v81
	v_pk_mul_f32 v[70:71], v[70:71], v[82:83] op_sel_hi:[1,0]
	v_cvt_pk_bf16_f32 v76, v76, v77
	v_cvt_pk_bf16_f32 v77, v84, v85
	flat_store_dwordx4 v[78:79], v[74:77]
	v_pk_mul_f32 v[72:73], v[72:73], v[82:83] op_sel_hi:[1,0]
	s_nop 0
	v_pk_mul_f32 v[74:75], v[68:69], v[82:83] op_sel_hi:[1,0]
	v_pk_mul_f32 v[68:69], v[66:67], v[82:83] op_sel_hi:[1,0]
	v_cvt_pk_bf16_f32 v66, v70, v71
	v_mad_i64_i32 v[70:71], s[0:1], v177, s33, v[122:123]
	v_lshl_add_u64 v[70:71], v[70:71], 0, s[90:91]
	v_cvt_pk_bf16_f32 v67, v72, v73
	v_lshl_add_u64 v[70:71], v[70:71], 0, v[0:1]
	v_cvt_pk_bf16_f32 v68, v68, v69
	v_cvt_pk_bf16_f32 v69, v74, v75
	flat_store_dwordx4 v[70:71], v[66:69]
	s_nop 1
	v_mov_b32_e32 v66, v143
	v_mov_b32_e32 v67, v144
	v_mov_b32_e32 v143, v145
	v_pk_add_f32 v[66:67], v[66:67], v[142:143]
	s_nop 0
	v_add_f32_e32 v66, v66, v67
	v_fmamk_f32 v66, v66, 0x3b800000, v218
	v_cmp_gt_f32_e32 vcc, s77, v66
	v_mul_f32_e32 v67, 0x4f800000, v66
	s_nop 0
	v_cndmask_b32_e32 v66, v66, v67, vcc
	v_sqrt_f32_e32 v67, v66
	s_nop 0
	v_add_u32_e32 v68, -1, v67
	v_fma_f32 v69, -v68, v67, v66
	v_cmp_ge_f32_e64 s[0:1], 0, v69
; __device__ __forceinline__ u32x4 pack8(const f32x4 v0, const f32x4 v1) { u32x4 w; w.x = cvt_pk_bf16(v0[0], v0[1]); w.y = cvt_pk_bf16(v0[2], v0[3]); w.z = cvt_pk_bf16(v1[0], v1[1]); w.w = cvt_pk_bf16(v1[2], v1[3]); return w; }
;     __device__ __forceinline__ void operator()(const f32x4 (&acc)[2][2][4][2], const Unit& u, int wr, int wc, int fr, int fq) const {
;     ...
;         for (int ai = 0; ai < 2; ++ai)
; #pragma unroll
;             for (int m = 0; m < 4; ++m) { const int row = row0 + ai * HALF + m * 16; const f32x4 a = q2[ai][m];
;                 const float s = 1.0f / sqrtf(((a[0] + a[1]) + (a[2] + a[3])) * (1.0f / 256.0f) + 1e-6f);
;                 *(u32x4*)(Kb + (size_t)row * ldk + 192 * u.pn + cin) = pack8(acc[ai][0][m][0] * s, acc[ai][0][m][1] * s);
;                 *(u32x4*)(Vb + (size_t)row * ldv + 128 * u.pn + cin) = pack8(acc[ai][1][m][0] * s, acc[ai][1][m][1] * s); }
	v_add_u32_e32 v69, 1, v67
	s_nop 0
	v_cndmask_b32_e64 v68, v67, v68, s[0:1]
	v_fma_f32 v67, -v69, v67, v66
	v_cmp_lt_f32_e64 s[0:1], 0, v67
	s_nop 1
	v_cndmask_b32_e64 v67, v68, v69, s[0:1]
	v_mul_f32_e32 v68, 0x37800000, v67
	v_cndmask_b32_e32 v67, v67, v68, vcc
	v_cmp_class_f32_e32 vcc, v66, v219
	s_nop 1
	v_cndmask_b32_e32 v66, v67, v66, vcc
	v_div_scale_f32 v67, s[0:1], v66, v66, 1.0
	v_rcp_f32_e32 v68, v67
	s_nop 0
	v_fma_f32 v69, -v67, v68, 1.0
	v_fmac_f32_e32 v68, v69, v68
	v_div_scale_f32 v69, vcc, 1.0, v66, 1.0
	v_mul_f32_e32 v70, v69, v68
	v_fma_f32 v71, -v67, v70, v69
	v_fmac_f32_e32 v70, v71, v68
	v_fma_f32 v67, -v67, v70, v69
	v_div_fmas_f32 v67, v67, v68, v70
	v_div_fixup_f32 v66, v67, v66, 1.0
	v_pk_mul_f32 v[62:63], v[62:63], v[66:67] op_sel_hi:[1,0]
	v_pk_mul_f32 v[68:69], v[60:61], v[66:67] op_sel_hi:[1,0]
	v_pk_mul_f32 v[60:61], v[58:59], v[66:67] op_sel_hi:[1,0]
	v_cvt_pk_bf16_f32 v58, v62, v63
	v_mad_i64_i32 v[62:63], s[0:1], v176, s87, v[134:135]
	v_lshl_add_u64 v[62:63], v[62:63], 0, s[28:29]
	v_pk_mul_f32 v[64:65], v[64:65], v[66:67] op_sel_hi:[1,0]
	v_lshl_add_u64 v[62:63], v[62:63], 0, v[0:1]
	v_cvt_pk_bf16_f32 v59, v64, v65
	v_pk_mul_f32 v[54:55], v[54:55], v[66:67] op_sel_hi:[1,0]
	v_cvt_pk_bf16_f32 v60, v60, v61
	v_cvt_pk_bf16_f32 v61, v68, v69
	flat_store_dwordx4 v[62:63], v[58:61]
	v_pk_mul_f32 v[56:57], v[56:57], v[66:67] op_sel_hi:[1,0]
	s_nop 0
	v_pk_mul_f32 v[58:59], v[52:53], v[66:67] op_sel_hi:[1,0]
	v_pk_mul_f32 v[52:53], v[50:51], v[66:67] op_sel_hi:[1,0]
	v_cvt_pk_bf16_f32 v50, v54, v55
	v_mad_i64_i32 v[54:55], s[0:1], v176, s33, v[122:123]
	v_lshl_add_u64 v[54:55], v[54:55], 0, s[90:91]
	v_cvt_pk_bf16_f32 v51, v56, v57
	v_lshl_add_u64 v[54:55], v[54:55], 0, v[0:1]
	v_cvt_pk_bf16_f32 v52, v52, v53
	v_cvt_pk_bf16_f32 v53, v58, v59
	flat_store_dwordx4 v[54:55], v[50:53]
	s_nop 1
	v_mov_b32_e32 v50, v131
	v_mov_b32_e32 v51, v132
	v_mov_b32_e32 v131, v133
	v_pk_add_f32 v[50:51], v[50:51], v[130:131]
	s_nop 0
	v_add_f32_e32 v50, v50, v51
	v_fmamk_f32 v50, v50, 0x3b800000, v218
	v_cmp_gt_f32_e32 vcc, s77, v50
	v_mul_f32_e32 v51, 0x4f800000, v50
	s_nop 0
	v_cndmask_b32_e32 v50, v50, v51, vcc
	v_sqrt_f32_e32 v51, v50
	s_nop 0
	v_add_u32_e32 v52, -1, v51
	v_fma_f32 v53, -v52, v51, v50
	v_cmp_ge_f32_e64 s[0:1], 0, v53
	v_add_u32_e32 v53, 1, v51
	s_nop 0
	v_cndmask_b32_e64 v52, v51, v52, s[0:1]
	v_fma_f32 v51, -v53, v51, v50
	v_cmp_lt_f32_e64 s[0:1], 0, v51
	s_nop 1
	v_cndmask_b32_e64 v51, v52, v53, s[0:1]
	v_mul_f32_e32 v52, 0x37800000, v51
	v_cndmask_b32_e32 v51, v51, v52, vcc
	v_cmp_class_f32_e32 vcc, v50, v219
	s_nop 1
	v_cndmask_b32_e32 v50, v51, v50, vcc
	v_div_scale_f32 v51, s[0:1], v50, v50, 1.0
	v_rcp_f32_e32 v52, v51
	s_nop 0
	v_fma_f32 v53, -v51, v52, 1.0
	v_fmac_f32_e32 v52, v53, v52
	v_div_scale_f32 v53, vcc, 1.0, v50, 1.0
	v_mul_f32_e32 v54, v53, v52
	v_fma_f32 v55, -v51, v54, v53
	v_fmac_f32_e32 v54, v55, v52
	v_fma_f32 v51, -v51, v54, v53
	v_div_fmas_f32 v51, v51, v52, v54
	v_div_fixup_f32 v50, v51, v50, 1.0
	v_pk_mul_f32 v[46:47], v[46:47], v[50:51] op_sel_hi:[1,0]
	v_pk_mul_f32 v[52:53], v[44:45], v[50:51] op_sel_hi:[1,0]
	v_pk_mul_f32 v[44:45], v[42:43], v[50:51] op_sel_hi:[1,0]
	v_cvt_pk_bf16_f32 v42, v46, v47
	v_mad_i64_i32 v[46:47], s[0:1], v175, s87, v[134:135]
	v_lshl_add_u64 v[46:47], v[46:47], 0, s[28:29]
	v_pk_mul_f32 v[48:49], v[48:49], v[50:51] op_sel_hi:[1,0]
	v_lshl_add_u64 v[46:47], v[46:47], 0, v[0:1]
	v_cvt_pk_bf16_f32 v43, v48, v49
	v_pk_mul_f32 v[38:39], v[38:39], v[50:51] op_sel_hi:[1,0]
	v_cvt_pk_bf16_f32 v44, v44, v45
	v_cvt_pk_bf16_f32 v45, v52, v53
	flat_store_dwordx4 v[46:47], v[42:45]
	v_pk_mul_f32 v[40:41], v[40:41], v[50:51] op_sel_hi:[1,0]
	s_nop 0
	v_pk_mul_f32 v[42:43], v[36:37], v[50:51] op_sel_hi:[1,0]
	v_pk_mul_f32 v[36:37], v[34:35], v[50:51] op_sel_hi:[1,0]
	v_cvt_pk_bf16_f32 v34, v38, v39
	v_mad_i64_i32 v[38:39], s[0:1], v175, s33, v[122:123]
	v_lshl_add_u64 v[38:39], v[38:39], 0, s[90:91]
	v_cvt_pk_bf16_f32 v35, v40, v41
	v_lshl_add_u64 v[38:39], v[38:39], 0, v[0:1]
	v_cvt_pk_bf16_f32 v36, v36, v37
	v_cvt_pk_bf16_f32 v37, v42, v43
	flat_store_dwordx4 v[38:39], v[34:37]
	s_nop 1
	v_mov_b32_e32 v34, v119
	v_mov_b32_e32 v35, v120
	v_mov_b32_e32 v119, v121
	v_pk_add_f32 v[34:35], v[34:35], v[118:119]
	s_nop 0
	v_add_f32_e32 v34, v34, v35
	v_fmamk_f32 v34, v34, 0x3b800000, v218
	v_cmp_gt_f32_e32 vcc, s77, v34
	v_mul_f32_e32 v35, 0x4f800000, v34
	s_nop 0
	v_cndmask_b32_e32 v34, v34, v35, vcc
	v_sqrt_f32_e32 v35, v34
	s_nop 0
	v_add_u32_e32 v36, -1, v35
	v_fma_f32 v37, -v36, v35, v34
	v_cmp_ge_f32_e64 s[0:1], 0, v37
	v_add_u32_e32 v37, 1, v35
	s_nop 0
	v_cndmask_b32_e64 v36, v35, v36, s[0:1]
	v_fma_f32 v35, -v37, v35, v34
	v_cmp_lt_f32_e64 s[0:1], 0, v35
	s_nop 1
	v_cndmask_b32_e64 v35, v36, v37, s[0:1]
; __device__ __forceinline__ u32x4 pack8(const f32x4 v0, const f32x4 v1) { u32x4 w; w.x = cvt_pk_bf16(v0[0], v0[1]); w.y = cvt_pk_bf16(v0[2], v0[3]); w.z = cvt_pk_bf16(v1[0], v1[1]); w.w = cvt_pk_bf16(v1[2], v1[3]); return w; }
; #define LAS __attribute__((address_space(3)))
;     __device__ __forceinline__ void operator()(const f32x4 (&acc)[2][2][4][2], const Unit& u, int wr, int wc, int fr, int fq) const {
;     ...
;         for (int ai = 0; ai < 2; ++ai)
; #pragma unroll
;             for (int m = 0; m < 4; ++m) { const int row = row0 + ai * HALF + m * 16; const f32x4 a = q2[ai][m];
;                 const float s = 1.0f / sqrtf(((a[0] + a[1]) + (a[2] + a[3])) * (1.0f / 256.0f) + 1e-6f);
;                 *(u32x4*)(Kb + (size_t)row * ldk + 192 * u.pn + cin) = pack8(acc[ai][0][m][0] * s, acc[ai][0][m][1] * s);
;                 *(u32x4*)(Vb + (size_t)row * ldv + 128 * u.pn + cin) = pack8(acc[ai][1][m][0] * s, acc[ai][1][m][1] * s); }
; template <int MODE>
; __device__ __forceinline__ void attn_unit(unsigned char* ws_, const float* rpb, const float* sink, int l, int h, int qb, int kvq, unsigned char* lds_g) {
;     ...
;   else if (MODE == 0) { const int R = qb * 4; T0 = min(max(R - 4, 0), 120); T1 = min(max(R - 1, 0), 120) + 8; wrow = R + (wid >> 1); tw0 = min(max(wrow - 4, 0), 120); tw1 = tw0 + 8;
;                         qcol = (wid & 1) * 32 + r32; c0 = min(max(qcol - 8, 0), 48); }
;   else { T0 = max(0, (q0 - 128) >> 6); T1 = min(S / 64, ((q0 + 255 + 128) >> 6) + 1); const int qw = q0 + wid * 32; tw0 = max(0, (qw - 128) >> 6); tw1 = min(S / 64, ((qw + 31 + 128) >> 6) + 1);
;          slope2 = exp2f(-8.0f * (float)(h + 1) / 6.0f) * LOG2E; }
;   LAS float* wsl = (LAS float*)(ldl + OFF_WS) + wid * 64; LAS float* li_l = wsl; LAS float* al_l = wsl + 32;
;   LAS float* rpbL = (LAS float*)(ldl + OFF_RPB);
;   if (MODE == 0) { for (int i = tid; i < 465; i += NTHREADS) rpbL[i] = rpb[(l * 4 + h) * 465 + i] * LOG2E; }
	v_mul_f32_e32 v36, 0x37800000, v35
	v_cndmask_b32_e32 v35, v35, v36, vcc
	v_cmp_class_f32_e32 vcc, v34, v219
	s_nop 1
	v_cndmask_b32_e32 v34, v35, v34, vcc
	v_div_scale_f32 v35, s[0:1], v34, v34, 1.0
	v_rcp_f32_e32 v36, v35
	s_nop 0
	v_fma_f32 v37, -v35, v36, 1.0
	v_fmac_f32_e32 v36, v37, v36
	v_div_scale_f32 v37, vcc, 1.0, v34, 1.0
	v_mul_f32_e32 v38, v37, v36
	v_fma_f32 v39, -v35, v38, v37
	v_fmac_f32_e32 v38, v39, v36
	v_fma_f32 v35, -v35, v38, v37
	v_div_fmas_f32 v35, v35, v36, v38
	v_div_fixup_f32 v34, v35, v34, 1.0
	v_pk_mul_f32 v[30:31], v[30:31], v[34:35] op_sel_hi:[1,0]
	v_pk_mul_f32 v[36:37], v[28:29], v[34:35] op_sel_hi:[1,0]
	v_pk_mul_f32 v[28:29], v[26:27], v[34:35] op_sel_hi:[1,0]
	v_cvt_pk_bf16_f32 v26, v30, v31
	v_mad_i64_i32 v[30:31], s[0:1], v174, s87, v[134:135]
	v_lshl_add_u64 v[30:31], v[30:31], 0, s[28:29]
	v_pk_mul_f32 v[32:33], v[32:33], v[34:35] op_sel_hi:[1,0]
	v_lshl_add_u64 v[30:31], v[30:31], 0, v[0:1]
	v_cvt_pk_bf16_f32 v27, v32, v33
	v_pk_mul_f32 v[22:23], v[22:23], v[34:35] op_sel_hi:[1,0]
	v_cvt_pk_bf16_f32 v28, v28, v29
	v_cvt_pk_bf16_f32 v29, v36, v37
	flat_store_dwordx4 v[30:31], v[26:29]
	v_pk_mul_f32 v[24:25], v[24:25], v[34:35] op_sel_hi:[1,0]
	s_nop 0
	v_pk_mul_f32 v[26:27], v[20:21], v[34:35] op_sel_hi:[1,0]
	v_pk_mul_f32 v[20:21], v[18:19], v[34:35] op_sel_hi:[1,0]
	v_cvt_pk_bf16_f32 v18, v22, v23
	v_mad_i64_i32 v[22:23], s[0:1], v174, s33, v[122:123]
	v_lshl_add_u64 v[22:23], v[22:23], 0, s[90:91]
	v_cvt_pk_bf16_f32 v19, v24, v25
	v_lshl_add_u64 v[22:23], v[22:23], 0, v[0:1]
	v_cvt_pk_bf16_f32 v20, v20, v21
	v_cvt_pk_bf16_f32 v21, v26, v27
	flat_store_dwordx4 v[22:23], v[18:21]
	s_nop 1
	v_mov_b32_e32 v18, v115
	v_mov_b32_e32 v19, v116
	v_mov_b32_e32 v115, v117
	v_pk_add_f32 v[18:19], v[18:19], v[114:115]
	s_nop 0
	v_add_f32_e32 v18, v18, v19
	v_fmamk_f32 v18, v18, 0x3b800000, v218
	v_cmp_gt_f32_e32 vcc, s77, v18
	v_mul_f32_e32 v19, 0x4f800000, v18
	s_nop 0
	v_cndmask_b32_e32 v18, v18, v19, vcc
	v_sqrt_f32_e32 v19, v18
	s_nop 0
	v_add_u32_e32 v20, -1, v19
	v_fma_f32 v21, -v20, v19, v18
	v_cmp_ge_f32_e64 s[0:1], 0, v21
	v_add_u32_e32 v21, 1, v19
	s_nop 0
	v_cndmask_b32_e64 v20, v19, v20, s[0:1]
	v_fma_f32 v19, -v21, v19, v18
	v_cmp_lt_f32_e64 s[0:1], 0, v19
	s_nop 1
	v_cndmask_b32_e64 v19, v20, v21, s[0:1]
	v_mul_f32_e32 v20, 0x37800000, v19
	v_cndmask_b32_e32 v19, v19, v20, vcc
	v_cmp_class_f32_e32 vcc, v18, v219
	s_nop 1
	v_cndmask_b32_e32 v18, v19, v18, vcc
	v_div_scale_f32 v19, s[0:1], v18, v18, 1.0
	v_rcp_f32_e32 v20, v19
	s_nop 0
	v_fma_f32 v21, -v19, v20, 1.0
	v_fmac_f32_e32 v20, v21, v20
	v_div_scale_f32 v21, vcc, 1.0, v18, 1.0
	v_mul_f32_e32 v22, v21, v20
	v_fma_f32 v23, -v19, v22, v21
	v_fmac_f32_e32 v22, v23, v20
	v_fma_f32 v19, -v19, v22, v21
	v_div_fmas_f32 v19, v19, v20, v22
	v_div_fixup_f32 v18, v19, v18, 1.0
	v_pk_mul_f32 v[14:15], v[14:15], v[18:19] op_sel_hi:[1,0]
	v_pk_mul_f32 v[20:21], v[12:13], v[18:19] op_sel_hi:[1,0]
	v_pk_mul_f32 v[12:13], v[10:11], v[18:19] op_sel_hi:[1,0]
	v_cvt_pk_bf16_f32 v10, v14, v15
	v_mad_i64_i32 v[14:15], s[0:1], v173, s87, v[134:135]
	v_lshl_add_u64 v[14:15], v[14:15], 0, s[28:29]
	v_pk_mul_f32 v[16:17], v[16:17], v[18:19] op_sel_hi:[1,0]
	v_lshl_add_u64 v[14:15], v[14:15], 0, v[0:1]
	v_cvt_pk_bf16_f32 v11, v16, v17
	v_pk_mul_f32 v[6:7], v[6:7], v[18:19] op_sel_hi:[1,0]
	v_cvt_pk_bf16_f32 v12, v12, v13
	v_cvt_pk_bf16_f32 v13, v20, v21
	flat_store_dwordx4 v[14:15], v[10:13]
	s_andn2_b64 vcc, exec, s[26:27]
	v_pk_mul_f32 v[8:9], v[8:9], v[18:19] op_sel_hi:[1,0]
	v_pk_mul_f32 v[10:11], v[4:5], v[18:19] op_sel_hi:[1,0]
	v_pk_mul_f32 v[4:5], v[2:3], v[18:19] op_sel_hi:[1,0]
	v_cvt_pk_bf16_f32 v2, v6, v7
	v_mad_i64_i32 v[6:7], s[0:1], v173, s33, v[122:123]
	v_lshl_add_u64 v[6:7], v[6:7], 0, s[90:91]
	v_lshl_add_u64 v[6:7], v[6:7], 0, v[0:1]
	s_mov_b64 s[0:1], -1
	v_cvt_pk_bf16_f32 v3, v8, v9
	v_cvt_pk_bf16_f32 v4, v4, v5
	v_cvt_pk_bf16_f32 v5, v10, v11
	flat_store_dwordx4 v[6:7], v[2:5]
	s_cbranch_vccnz .LBB0_674
	s_andn2_b64 vcc, exec, s[8:9]
	s_cbranch_vccnz .LBB0_673
	s_barrier
	s_branch .LBB0_673
.LBB0_683:
	s_waitcnt lgkmcnt(0)
	s_barrier
.LBB0_684:
	s_cmp_lt_i32 s30, 0
	s_cbranch_scc1 .LBB0_777
	v_readlane_b32 s0, v254, 43
	v_mov_b32_e32 v8, v216
	s_movk_i32 s2, 0x1d1
	v_mov_b32_e32 v0, s0
	ds_read_b64 v[2:3], v0
	v_readlane_b32 s0, v254, 22
	s_lshr_b32 s6, s30, 5
	s_waitcnt lgkmcnt(0)
	v_readfirstlane_b32 s94, v2
	v_mov_b32_e32 v0, s0
	v_readfirstlane_b32 s95, v3
	ds_read_b64 v[2:3], v0
	s_waitcnt lgkmcnt(0)
	v_readfirstlane_b32 s0, v2
	v_readfirstlane_b32 s1, v3
	v_cmp_gt_i32_e32 vcc, s2, v8
	s_and_saveexec_b64 s[2:3], vcc
	s_cbranch_execz .LBB0_688
	v_readlane_b32 s4, v254, 50
	s_add_i32 s7, s6, s4
	v_readlane_b32 s4, v254, 23
	s_mulk_i32 s7, 0x1d1
	v_mov_b32_e32 v2, v8
	v_lshl_add_u32 v0, v8, 2, s4
	s_mov_b64 s[4:5], 0
